# w_in epilogue: preload 8 row sums per column block instead of 16 serialised load-wait-store round trips (on top of transpose fix)
# speedup vs baseline: 1.0270x; 1.0193x over previous
; __device__ __forceinline__ unsigned cvtpk(float lo, float hi) { f32x2 v = {lo, hi}; bf16x2_t b = __builtin_convertvector(v, bf16x2_t); return __builtin_bit_cast(unsigned, b); }
;     __device__ __forceinline__ void operator()(const pg8::f32x4 (&acc)[2][2][4][2], const pg8::Unit& u, int wr, int wc, int fr, int fq) const {
;     ...
;         } else if (kind == EK_BF16 && PERM) {
; #pragma unroll
;             for (int bj = 0; bj < 2; ++bj) {
;                 const int c = colb + 128 * bj;
;                 if (c < ncols) {
; #pragma unroll
;                     for (int ai = 0; ai < 2; ++ai)
; #pragma unroll
;                         for (int m = 0; m < 4; ++m) {
;                             pg8::f32x4 v0 = acc[ai][bj][m][0], v1 = acc[ai][bj][m][1];
;                             if (flags & 4) { const float rs = __builtin_amdgcn_rsqf(fin[rowb + 128 * ai + 16 * m] * (1.0f / DM) + EPS); v0 = v0 * rs; v1 = v1 * rs; }
;                             *(u32x4*)(o0 + (size_t)(rowb + 128 * ai + 16 * m) * ldc + c) = (u32x4){cvtpk(v0[0], v0[1]), cvtpk(v0[2], v0[3]), cvtpk(v1[0], v1[1]), cvtpk(v1[2], v1[3])};
;                         }
;                 }
;             }
.LBB0_1143:
	global_load_dwordx4 v[64:67], v215, s[40:41] offset:1024
	global_load_dwordx4 v[68:71], v215, s[40:41] offset:1064
	global_load_dwordx4 v[136:139], v215, s[40:41] offset:1048
	v_lshl_add_u32 v228, s8, 8, v252
	s_mov_b64 s[8:9], -1
	s_waitcnt vmcnt(0)
	v_readfirstlane_b32 s47, v64
	s_cmp_lt_i32 s47, 1
	s_cbranch_scc1 .LBB0_1235
	v_lshl_or_b32 v230, s54, 8, v248
	s_cmp_lt_i32 s47, 2
	s_cbranch_scc1 .LBB0_1184
	s_cmp_eq_u32 s47, 2
	s_cbranch_scc0 .LBB0_1183
	v_and_b32_e32 v64, 4, v67
	v_cmp_ne_u32_e64 s[8:9], 0, v64
	v_cmp_lt_i32_e32 vcc, v230, v66
	s_nop 0
	v_cndmask_b32_e64 v64, 0, 1, s[8:9]
	v_cmp_ne_u32_e64 s[8:9], 1, v64
	s_and_saveexec_b64 s[10:11], vcc
	s_cbranch_execz .LBB0_1164
	v_ashrrev_i32_e32 v229, 31, v228
	v_mov_b64_e32 v[142:143], v[134:135]
	v_mov_b64_e32 v[146:147], v[130:131]
	s_and_b64 vcc, exec, s[8:9]
	v_lshl_add_u64 v[150:151], v[228:229], 2, v[136:137]
	v_mov_b64_e32 v[140:141], v[132:133]
	v_mov_b64_e32 v[144:145], v[128:129]
	s_cbranch_vccnz .Lepi_pre_skip_1
	global_load_dword v152, v[150:151], off
	global_load_dword v153, v[150:151], off offset:64
	global_load_dword v154, v[150:151], off offset:128
	global_load_dword v155, v[150:151], off offset:192
	global_load_dword v156, v[150:151], off offset:512
	global_load_dword v157, v[150:151], off offset:576
	global_load_dword v158, v[150:151], off offset:640
	global_load_dword v159, v[150:151], off offset:704
	s_waitcnt vmcnt(0)
.Lepi_pre_skip_1:
	s_cbranch_vccnz .LBB0_1149
	v_mov_b32_e32 v64, v152
	v_fmamk_f32 v64, v64, 0x3a800000, v244
	v_rsq_f32_e32 v64, v64
	s_nop 0
	v_pk_mul_f32 v[142:143], v[134:135], v[64:65] op_sel_hi:[1,0]
	v_pk_mul_f32 v[140:141], v[132:133], v[64:65] op_sel_hi:[1,0]
	v_pk_mul_f32 v[146:147], v[130:131], v[64:65] op_sel_hi:[1,0]
	v_pk_mul_f32 v[144:145], v[128:129], v[64:65] op_sel_hi:[1,0]
.LBB0_1149:
	v_ashrrev_i32_e32 v231, 31, v230
	v_lshl_add_u64 v[148:149], v[230:231], 1, v[68:69]
	v_cvt_pk_bf16_f32 v140, v140, v141
	v_cvt_pk_bf16_f32 v141, v142, v143
	v_cvt_pk_bf16_f32 v142, v144, v145
	v_mad_i64_i32 v[144:145], s[18:19], v65, v228, 0
	v_cvt_pk_bf16_f32 v143, v146, v147
	v_lshl_add_u64 v[144:145], v[144:145], 1, v[148:149]
	global_store_dwordx4 v[144:145], v[140:143], off
	v_mov_b64_e32 v[146:147], v[110:111]
	s_and_b64 vcc, exec, s[8:9]
	v_mov_b64_e32 v[142:143], v[118:119]
	v_mov_b64_e32 v[140:141], v[116:117]
	v_mov_b64_e32 v[144:145], v[108:109]
	s_cbranch_vccnz .LBB0_1151
	v_mov_b32_e32 v64, v153
	v_fmamk_f32 v64, v64, 0x3a800000, v244
	v_rsq_f32_e32 v64, v64
	s_nop 0
	v_pk_mul_f32 v[142:143], v[118:119], v[64:65] op_sel_hi:[1,0]
	v_pk_mul_f32 v[140:141], v[116:117], v[64:65] op_sel_hi:[1,0]
	v_pk_mul_f32 v[146:147], v[110:111], v[64:65] op_sel_hi:[1,0]
	v_pk_mul_f32 v[144:145], v[108:109], v[64:65] op_sel_hi:[1,0]
.LBB0_1151:
	v_or_b32_e32 v64, 16, v228
	v_cvt_pk_bf16_f32 v140, v140, v141
	v_cvt_pk_bf16_f32 v141, v142, v143
	v_cvt_pk_bf16_f32 v142, v144, v145
	v_mad_i64_i32 v[144:145], s[18:19], v65, v64, 0
	v_cvt_pk_bf16_f32 v143, v146, v147
	v_lshl_add_u64 v[144:145], v[144:145], 1, v[148:149]
	global_store_dwordx4 v[144:145], v[140:143], off
	v_mov_b64_e32 v[146:147], v[94:95]
	s_and_b64 vcc, exec, s[8:9]
	v_mov_b64_e32 v[142:143], v[102:103]
	v_mov_b64_e32 v[140:141], v[100:101]
	v_mov_b64_e32 v[144:145], v[92:93]
	s_cbranch_vccnz .LBB0_1153
	v_mov_b32_e32 v64, v154
	v_fmamk_f32 v64, v64, 0x3a800000, v244
	v_rsq_f32_e32 v64, v64
	s_nop 0
	v_pk_mul_f32 v[142:143], v[102:103], v[64:65] op_sel_hi:[1,0]
	v_pk_mul_f32 v[140:141], v[100:101], v[64:65] op_sel_hi:[1,0]
	v_pk_mul_f32 v[146:147], v[94:95], v[64:65] op_sel_hi:[1,0]
	v_pk_mul_f32 v[144:145], v[92:93], v[64:65] op_sel_hi:[1,0]
; __device__ __forceinline__ unsigned cvtpk(float lo, float hi) { f32x2 v = {lo, hi}; bf16x2_t b = __builtin_convertvector(v, bf16x2_t); return __builtin_bit_cast(unsigned, b); }
;     __device__ __forceinline__ void operator()(const pg8::f32x4 (&acc)[2][2][4][2], const pg8::Unit& u, int wr, int wc, int fr, int fq) const {
;     ...
;         } else if (kind == EK_BF16 && PERM) {
; #pragma unroll
;             for (int bj = 0; bj < 2; ++bj) {
;                 const int c = colb + 128 * bj;
;                 if (c < ncols) {
; #pragma unroll
;                     for (int ai = 0; ai < 2; ++ai)
; #pragma unroll
;                         for (int m = 0; m < 4; ++m) {
;                             pg8::f32x4 v0 = acc[ai][bj][m][0], v1 = acc[ai][bj][m][1];
;                             if (flags & 4) { const float rs = __builtin_amdgcn_rsqf(fin[rowb + 128 * ai + 16 * m] * (1.0f / DM) + EPS); v0 = v0 * rs; v1 = v1 * rs; }
;                             *(u32x4*)(o0 + (size_t)(rowb + 128 * ai + 16 * m) * ldc + c) = (u32x4){cvtpk(v0[0], v0[1]), cvtpk(v0[2], v0[3]), cvtpk(v1[0], v1[1]), cvtpk(v1[2], v1[3])};
;                         }
;                 }
;             }
.LBB0_1153:
	v_or_b32_e32 v64, 32, v228
	v_cvt_pk_bf16_f32 v140, v140, v141
	v_cvt_pk_bf16_f32 v141, v142, v143
	v_cvt_pk_bf16_f32 v142, v144, v145
	v_mad_i64_i32 v[144:145], s[18:19], v65, v64, 0
	v_cvt_pk_bf16_f32 v143, v146, v147
	v_lshl_add_u64 v[144:145], v[144:145], 1, v[148:149]
	global_store_dwordx4 v[144:145], v[140:143], off
	v_mov_b64_e32 v[146:147], v[78:79]
	s_and_b64 vcc, exec, s[8:9]
	v_mov_b64_e32 v[142:143], v[86:87]
	v_mov_b64_e32 v[140:141], v[84:85]
	v_mov_b64_e32 v[144:145], v[76:77]
	s_cbranch_vccnz .LBB0_1155
	v_mov_b32_e32 v64, v155
	v_fmamk_f32 v64, v64, 0x3a800000, v244
	v_rsq_f32_e32 v64, v64
	s_nop 0
	v_pk_mul_f32 v[142:143], v[86:87], v[64:65] op_sel_hi:[1,0]
	v_pk_mul_f32 v[140:141], v[84:85], v[64:65] op_sel_hi:[1,0]
	v_pk_mul_f32 v[146:147], v[78:79], v[64:65] op_sel_hi:[1,0]
	v_pk_mul_f32 v[144:145], v[76:77], v[64:65] op_sel_hi:[1,0]
.LBB0_1155:
	v_or_b32_e32 v64, 48, v228
	v_cvt_pk_bf16_f32 v140, v140, v141
	v_cvt_pk_bf16_f32 v141, v142, v143
	v_cvt_pk_bf16_f32 v142, v144, v145
	v_mad_i64_i32 v[144:145], s[18:19], v65, v64, 0
	v_cvt_pk_bf16_f32 v143, v146, v147
	v_lshl_add_u64 v[144:145], v[144:145], 1, v[148:149]
	global_store_dwordx4 v[144:145], v[140:143], off
	v_mov_b64_e32 v[146:147], v[54:55]
	s_and_b64 vcc, exec, s[8:9]
	v_mov_b64_e32 v[142:143], v[62:63]
	v_mov_b64_e32 v[140:141], v[60:61]
	v_mov_b64_e32 v[144:145], v[52:53]
	s_cbranch_vccnz .LBB0_1157
	v_mov_b32_e32 v64, v156
	v_fmamk_f32 v64, v64, 0x3a800000, v244
	v_rsq_f32_e32 v64, v64
	s_nop 0
	v_pk_mul_f32 v[142:143], v[62:63], v[64:65] op_sel_hi:[1,0]
	v_pk_mul_f32 v[140:141], v[60:61], v[64:65] op_sel_hi:[1,0]
	v_pk_mul_f32 v[146:147], v[54:55], v[64:65] op_sel_hi:[1,0]
	v_pk_mul_f32 v[144:145], v[52:53], v[64:65] op_sel_hi:[1,0]
.LBB0_1157:
	v_add_u32_e32 v64, 0x80, v228
	v_cvt_pk_bf16_f32 v140, v140, v141
	v_cvt_pk_bf16_f32 v141, v142, v143
	v_cvt_pk_bf16_f32 v142, v144, v145
	v_mad_i64_i32 v[144:145], s[18:19], v65, v64, 0
	v_cvt_pk_bf16_f32 v143, v146, v147
	v_lshl_add_u64 v[144:145], v[144:145], 1, v[148:149]
	global_store_dwordx4 v[144:145], v[140:143], off
	v_mov_b64_e32 v[146:147], v[38:39]
	s_and_b64 vcc, exec, s[8:9]
	v_mov_b64_e32 v[142:143], v[46:47]
	v_mov_b64_e32 v[140:141], v[44:45]
	v_mov_b64_e32 v[144:145], v[36:37]
	s_cbranch_vccnz .LBB0_1159
	v_mov_b32_e32 v64, v157
	v_fmamk_f32 v64, v64, 0x3a800000, v244
	v_rsq_f32_e32 v64, v64
	s_nop 0
	v_pk_mul_f32 v[142:143], v[46:47], v[64:65] op_sel_hi:[1,0]
	v_pk_mul_f32 v[140:141], v[44:45], v[64:65] op_sel_hi:[1,0]
	v_pk_mul_f32 v[146:147], v[38:39], v[64:65] op_sel_hi:[1,0]
	v_pk_mul_f32 v[144:145], v[36:37], v[64:65] op_sel_hi:[1,0]
.LBB0_1159:
	v_add_u32_e32 v64, 0x90, v228
	v_cvt_pk_bf16_f32 v140, v140, v141
	v_cvt_pk_bf16_f32 v141, v142, v143
	v_cvt_pk_bf16_f32 v142, v144, v145
	v_mad_i64_i32 v[144:145], s[18:19], v65, v64, 0
	v_cvt_pk_bf16_f32 v143, v146, v147
	v_lshl_add_u64 v[144:145], v[144:145], 1, v[148:149]
	global_store_dwordx4 v[144:145], v[140:143], off
	v_mov_b64_e32 v[146:147], v[22:23]
	s_and_b64 vcc, exec, s[8:9]
	v_mov_b64_e32 v[142:143], v[30:31]
	v_mov_b64_e32 v[140:141], v[28:29]
	v_mov_b64_e32 v[144:145], v[20:21]
	s_cbranch_vccnz .LBB0_1161
	v_mov_b32_e32 v64, v158
	v_fmamk_f32 v64, v64, 0x3a800000, v244
	v_rsq_f32_e32 v64, v64
	s_nop 0
	v_pk_mul_f32 v[142:143], v[30:31], v[64:65] op_sel_hi:[1,0]
	v_pk_mul_f32 v[140:141], v[28:29], v[64:65] op_sel_hi:[1,0]
	v_pk_mul_f32 v[146:147], v[22:23], v[64:65] op_sel_hi:[1,0]
	v_pk_mul_f32 v[144:145], v[20:21], v[64:65] op_sel_hi:[1,0]
.LBB0_1161:
	v_add_u32_e32 v64, 0xa0, v228
	v_cvt_pk_bf16_f32 v140, v140, v141
	v_cvt_pk_bf16_f32 v141, v142, v143
	v_cvt_pk_bf16_f32 v142, v144, v145
	v_mad_i64_i32 v[144:145], s[18:19], v65, v64, 0
	v_cvt_pk_bf16_f32 v143, v146, v147
	v_lshl_add_u64 v[144:145], v[144:145], 1, v[148:149]
	global_store_dwordx4 v[144:145], v[140:143], off
	v_mov_b64_e32 v[146:147], v[6:7]
	s_and_b64 vcc, exec, s[8:9]
	v_mov_b64_e32 v[142:143], v[14:15]
	v_mov_b64_e32 v[140:141], v[12:13]
	v_mov_b64_e32 v[144:145], v[4:5]
	s_cbranch_vccnz .LBB0_1163
	v_mov_b32_e32 v64, v159
	v_fmamk_f32 v64, v64, 0x3a800000, v244
	v_rsq_f32_e32 v64, v64
	s_nop 0
	v_pk_mul_f32 v[142:143], v[14:15], v[64:65] op_sel_hi:[1,0]
	v_pk_mul_f32 v[140:141], v[12:13], v[64:65] op_sel_hi:[1,0]
	v_pk_mul_f32 v[146:147], v[6:7], v[64:65] op_sel_hi:[1,0]
	v_pk_mul_f32 v[144:145], v[4:5], v[64:65] op_sel_hi:[1,0]

; __device__ __forceinline__ unsigned cvtpk(float lo, float hi) { f32x2 v = {lo, hi}; bf16x2_t b = __builtin_convertvector(v, bf16x2_t); return __builtin_bit_cast(unsigned, b); }
;     __device__ __forceinline__ void operator()(const pg8::f32x4 (&acc)[2][2][4][2], const pg8::Unit& u, int wr, int wc, int fr, int fq) const {
;     ...
;         } else if (kind == EK_BF16 && PERM) {
; #pragma unroll
;             for (int bj = 0; bj < 2; ++bj) {
;                 const int c = colb + 128 * bj;
;                 if (c < ncols) {
; #pragma unroll
;                     for (int ai = 0; ai < 2; ++ai)
; #pragma unroll
;                         for (int m = 0; m < 4; ++m) {
;                             pg8::f32x4 v0 = acc[ai][bj][m][0], v1 = acc[ai][bj][m][1];
;                             if (flags & 4) { const float rs = __builtin_amdgcn_rsqf(fin[rowb + 128 * ai + 16 * m] * (1.0f / DM) + EPS); v0 = v0 * rs; v1 = v1 * rs; }
;                             *(u32x4*)(o0 + (size_t)(rowb + 128 * ai + 16 * m) * ldc + c) = (u32x4){cvtpk(v0[0], v0[1]), cvtpk(v0[2], v0[3]), cvtpk(v1[0], v1[1]), cvtpk(v1[2], v1[3])};
;                         }
;                 }
;             }
.LBB0_1164:
	s_or_b64 exec, exec, s[10:11]
	v_or_b32_e32 v64, 0x80, v230
	v_cmp_lt_i32_e32 vcc, v64, v66
	s_and_saveexec_b64 s[10:11], vcc
	s_cbranch_execz .LBB0_1182
	v_ashrrev_i32_e32 v229, 31, v228
	v_mov_b64_e32 v[142:143], v[126:127]
	v_mov_b64_e32 v[146:147], v[122:123]
	s_and_b64 vcc, exec, s[8:9]
	v_lshl_add_u64 v[150:151], v[228:229], 2, v[136:137]
	v_mov_b64_e32 v[140:141], v[124:125]
	v_mov_b64_e32 v[144:145], v[120:121]
	s_cbranch_vccnz .Lepi_pre_skip_2
	global_load_dword v152, v[150:151], off
	global_load_dword v153, v[150:151], off offset:64
	global_load_dword v154, v[150:151], off offset:128
	global_load_dword v155, v[150:151], off offset:192
	global_load_dword v156, v[150:151], off offset:512
	global_load_dword v157, v[150:151], off offset:576
	global_load_dword v158, v[150:151], off offset:640
	global_load_dword v159, v[150:151], off offset:704
	s_waitcnt vmcnt(0)
.Lepi_pre_skip_2:
	s_cbranch_vccnz .LBB0_1167
	v_mov_b32_e32 v64, v152
	v_fmamk_f32 v64, v64, 0x3a800000, v244
	v_rsq_f32_e32 v64, v64
	s_nop 0
	v_pk_mul_f32 v[142:143], v[126:127], v[64:65] op_sel_hi:[1,0]
	v_pk_mul_f32 v[140:141], v[124:125], v[64:65] op_sel_hi:[1,0]
	v_pk_mul_f32 v[146:147], v[122:123], v[64:65] op_sel_hi:[1,0]
	v_pk_mul_f32 v[144:145], v[120:121], v[64:65] op_sel_hi:[1,0]
.LBB0_1167:
	v_ashrrev_i32_e32 v231, 31, v230
	v_lshl_add_u64 v[148:149], v[230:231], 1, v[68:69]
	v_cvt_pk_bf16_f32 v140, v140, v141
	v_cvt_pk_bf16_f32 v141, v142, v143
	v_cvt_pk_bf16_f32 v142, v144, v145
	v_mad_i64_i32 v[144:145], s[18:19], v65, v228, 0
	v_cvt_pk_bf16_f32 v143, v146, v147
	v_lshl_add_u64 v[144:145], v[144:145], 1, v[148:149]
	global_store_dwordx4 v[144:145], v[140:143], off offset:256
	v_mov_b64_e32 v[146:147], v[106:107]
	s_and_b64 vcc, exec, s[8:9]
	v_mov_b64_e32 v[142:143], v[114:115]
	v_mov_b64_e32 v[140:141], v[112:113]
	v_mov_b64_e32 v[144:145], v[104:105]
	s_cbranch_vccnz .LBB0_1169
	v_mov_b32_e32 v64, v153
	v_fmamk_f32 v64, v64, 0x3a800000, v244
	v_rsq_f32_e32 v64, v64
	s_nop 0
	v_pk_mul_f32 v[142:143], v[114:115], v[64:65] op_sel_hi:[1,0]
	v_pk_mul_f32 v[140:141], v[112:113], v[64:65] op_sel_hi:[1,0]
	v_pk_mul_f32 v[146:147], v[106:107], v[64:65] op_sel_hi:[1,0]
	v_pk_mul_f32 v[144:145], v[104:105], v[64:65] op_sel_hi:[1,0]
.LBB0_1169:
	v_or_b32_e32 v64, 16, v228
	v_cvt_pk_bf16_f32 v140, v140, v141
	v_cvt_pk_bf16_f32 v141, v142, v143
	v_cvt_pk_bf16_f32 v142, v144, v145
	v_mad_i64_i32 v[144:145], s[18:19], v65, v64, 0
	v_cvt_pk_bf16_f32 v143, v146, v147
	v_lshl_add_u64 v[144:145], v[144:145], 1, v[148:149]
	global_store_dwordx4 v[144:145], v[140:143], off offset:256
	v_mov_b64_e32 v[146:147], v[90:91]
	s_and_b64 vcc, exec, s[8:9]
	v_mov_b64_e32 v[142:143], v[98:99]
	v_mov_b64_e32 v[140:141], v[96:97]
	v_mov_b64_e32 v[144:145], v[88:89]
	s_cbranch_vccnz .LBB0_1171
	v_mov_b32_e32 v64, v154
	v_fmamk_f32 v64, v64, 0x3a800000, v244
	v_rsq_f32_e32 v64, v64
	s_nop 0
	v_pk_mul_f32 v[142:143], v[98:99], v[64:65] op_sel_hi:[1,0]
	v_pk_mul_f32 v[140:141], v[96:97], v[64:65] op_sel_hi:[1,0]
	v_pk_mul_f32 v[146:147], v[90:91], v[64:65] op_sel_hi:[1,0]
	v_pk_mul_f32 v[144:145], v[88:89], v[64:65] op_sel_hi:[1,0]
.LBB0_1171:
	v_or_b32_e32 v64, 32, v228
	v_cvt_pk_bf16_f32 v140, v140, v141
	v_cvt_pk_bf16_f32 v141, v142, v143
	v_cvt_pk_bf16_f32 v142, v144, v145
	v_mad_i64_i32 v[144:145], s[18:19], v65, v64, 0
	v_cvt_pk_bf16_f32 v143, v146, v147
	v_lshl_add_u64 v[144:145], v[144:145], 1, v[148:149]
	global_store_dwordx4 v[144:145], v[140:143], off offset:256
	v_mov_b64_e32 v[146:147], v[74:75]
	s_and_b64 vcc, exec, s[8:9]
	v_mov_b64_e32 v[142:143], v[82:83]
	v_mov_b64_e32 v[140:141], v[80:81]
	v_mov_b64_e32 v[144:145], v[72:73]
	s_cbranch_vccnz .LBB0_1173
	v_mov_b32_e32 v64, v155
	v_fmamk_f32 v64, v64, 0x3a800000, v244
	v_rsq_f32_e32 v64, v64
	s_nop 0
	v_pk_mul_f32 v[142:143], v[82:83], v[64:65] op_sel_hi:[1,0]
	v_pk_mul_f32 v[140:141], v[80:81], v[64:65] op_sel_hi:[1,0]
	v_pk_mul_f32 v[146:147], v[74:75], v[64:65] op_sel_hi:[1,0]
	v_pk_mul_f32 v[144:145], v[72:73], v[64:65] op_sel_hi:[1,0]
; __device__ __forceinline__ unsigned cvtpk(float lo, float hi) { f32x2 v = {lo, hi}; bf16x2_t b = __builtin_convertvector(v, bf16x2_t); return __builtin_bit_cast(unsigned, b); }
;     __device__ __forceinline__ void operator()(const pg8::f32x4 (&acc)[2][2][4][2], const pg8::Unit& u, int wr, int wc, int fr, int fq) const {
;     ...
;         } else if (kind == EK_BF16 && PERM) {
; #pragma unroll
;             for (int bj = 0; bj < 2; ++bj) {
;                 const int c = colb + 128 * bj;
;                 if (c < ncols) {
; #pragma unroll
;                     for (int ai = 0; ai < 2; ++ai)
; #pragma unroll
;                         for (int m = 0; m < 4; ++m) {
;                             pg8::f32x4 v0 = acc[ai][bj][m][0], v1 = acc[ai][bj][m][1];
;                             if (flags & 4) { const float rs = __builtin_amdgcn_rsqf(fin[rowb + 128 * ai + 16 * m] * (1.0f / DM) + EPS); v0 = v0 * rs; v1 = v1 * rs; }
;                             *(u32x4*)(o0 + (size_t)(rowb + 128 * ai + 16 * m) * ldc + c) = (u32x4){cvtpk(v0[0], v0[1]), cvtpk(v0[2], v0[3]), cvtpk(v1[0], v1[1]), cvtpk(v1[2], v1[3])};
;                         }
;                 }
;             }
.LBB0_1173:
	v_or_b32_e32 v64, 48, v228
	v_cvt_pk_bf16_f32 v140, v140, v141
	v_cvt_pk_bf16_f32 v141, v142, v143
	v_cvt_pk_bf16_f32 v142, v144, v145
	v_mad_i64_i32 v[144:145], s[18:19], v65, v64, 0
	v_cvt_pk_bf16_f32 v143, v146, v147
	v_lshl_add_u64 v[144:145], v[144:145], 1, v[148:149]
	global_store_dwordx4 v[144:145], v[140:143], off offset:256
	v_mov_b64_e32 v[146:147], v[50:51]
	s_and_b64 vcc, exec, s[8:9]
	v_mov_b64_e32 v[142:143], v[58:59]
	v_mov_b64_e32 v[140:141], v[56:57]
	v_mov_b64_e32 v[144:145], v[48:49]
	s_cbranch_vccnz .LBB0_1175
	v_mov_b32_e32 v64, v156
	v_fmamk_f32 v64, v64, 0x3a800000, v244
	v_rsq_f32_e32 v64, v64
	s_nop 0
	v_pk_mul_f32 v[142:143], v[58:59], v[64:65] op_sel_hi:[1,0]
	v_pk_mul_f32 v[140:141], v[56:57], v[64:65] op_sel_hi:[1,0]
	v_pk_mul_f32 v[146:147], v[50:51], v[64:65] op_sel_hi:[1,0]
	v_pk_mul_f32 v[144:145], v[48:49], v[64:65] op_sel_hi:[1,0]
.LBB0_1175:
	v_add_u32_e32 v64, 0x80, v228
	v_cvt_pk_bf16_f32 v140, v140, v141
	v_cvt_pk_bf16_f32 v141, v142, v143
	v_cvt_pk_bf16_f32 v142, v144, v145
	v_mad_i64_i32 v[144:145], s[18:19], v65, v64, 0
	v_cvt_pk_bf16_f32 v143, v146, v147
	v_lshl_add_u64 v[144:145], v[144:145], 1, v[148:149]
	global_store_dwordx4 v[144:145], v[140:143], off offset:256
	v_mov_b64_e32 v[146:147], v[34:35]
	s_and_b64 vcc, exec, s[8:9]
	v_mov_b64_e32 v[142:143], v[42:43]
	v_mov_b64_e32 v[140:141], v[40:41]
	v_mov_b64_e32 v[144:145], v[32:33]
	s_cbranch_vccnz .LBB0_1177
	v_mov_b32_e32 v64, v157
	v_fmamk_f32 v64, v64, 0x3a800000, v244
	v_rsq_f32_e32 v64, v64
	s_nop 0
	v_pk_mul_f32 v[142:143], v[42:43], v[64:65] op_sel_hi:[1,0]
	v_pk_mul_f32 v[140:141], v[40:41], v[64:65] op_sel_hi:[1,0]
	v_pk_mul_f32 v[146:147], v[34:35], v[64:65] op_sel_hi:[1,0]
	v_pk_mul_f32 v[144:145], v[32:33], v[64:65] op_sel_hi:[1,0]
.LBB0_1177:
	v_add_u32_e32 v64, 0x90, v228
	v_cvt_pk_bf16_f32 v140, v140, v141
	v_cvt_pk_bf16_f32 v141, v142, v143
	v_cvt_pk_bf16_f32 v142, v144, v145
	v_mad_i64_i32 v[144:145], s[18:19], v65, v64, 0
	v_cvt_pk_bf16_f32 v143, v146, v147
	v_lshl_add_u64 v[144:145], v[144:145], 1, v[148:149]
	global_store_dwordx4 v[144:145], v[140:143], off offset:256
	v_mov_b64_e32 v[146:147], v[18:19]
	s_and_b64 vcc, exec, s[8:9]
	v_mov_b64_e32 v[142:143], v[26:27]
	v_mov_b64_e32 v[140:141], v[24:25]
	v_mov_b64_e32 v[144:145], v[16:17]
	s_cbranch_vccnz .LBB0_1179
	v_mov_b32_e32 v64, v158
	v_fmamk_f32 v64, v64, 0x3a800000, v244
	v_rsq_f32_e32 v64, v64
	s_nop 0
	v_pk_mul_f32 v[142:143], v[26:27], v[64:65] op_sel_hi:[1,0]
	v_pk_mul_f32 v[140:141], v[24:25], v[64:65] op_sel_hi:[1,0]
	v_pk_mul_f32 v[146:147], v[18:19], v[64:65] op_sel_hi:[1,0]
	v_pk_mul_f32 v[144:145], v[16:17], v[64:65] op_sel_hi:[1,0]
.LBB0_1179:
	v_add_u32_e32 v64, 0xa0, v228
	v_cvt_pk_bf16_f32 v140, v140, v141
	v_cvt_pk_bf16_f32 v141, v142, v143
	v_cvt_pk_bf16_f32 v142, v144, v145
	v_mad_i64_i32 v[144:145], s[18:19], v65, v64, 0
	v_cvt_pk_bf16_f32 v143, v146, v147
	v_lshl_add_u64 v[144:145], v[144:145], 1, v[148:149]
	global_store_dwordx4 v[144:145], v[140:143], off offset:256
	v_mov_b64_e32 v[146:147], v[2:3]
	s_and_b64 vcc, exec, s[8:9]
	v_mov_b64_e32 v[142:143], v[10:11]
	v_mov_b64_e32 v[140:141], v[8:9]
	v_mov_b64_e32 v[144:145], v[0:1]
	s_cbranch_vccnz .LBB0_1181
	v_mov_b32_e32 v64, v159
	v_fmamk_f32 v64, v64, 0x3a800000, v244
	v_rsq_f32_e32 v64, v64
	s_nop 0
	v_pk_mul_f32 v[142:143], v[10:11], v[64:65] op_sel_hi:[1,0]
	v_pk_mul_f32 v[140:141], v[8:9], v[64:65] op_sel_hi:[1,0]
	v_pk_mul_f32 v[146:147], v[2:3], v[64:65] op_sel_hi:[1,0]
	v_pk_mul_f32 v[144:145], v[0:1], v[64:65] op_sel_hi:[1,0]
